# P0 weight loop read-back: the two LDS reads of each group issued together with counted lgkmcnt waits; on top of the previous best
# speedup vs baseline: 1.0098x; 1.0038x over previous
; #define LAS __attribute__((address_space(3)))
; DI unsigned cvt_pk_bf16(float lo, float hi) { unsigned r; asm volatile("v_cvt_pk_bf16_f32 %0, %1, %2" : "=v"(r) : "v"(lo), "v"(hi)); return r; }
; DI void transpose_w(const float* __restrict__ w, const float* __restrict__ rowscale, bf16_t* __restrict__ out, int K, int N, int bid, int nb, LAS float* tile) {
;     ...
;         for (int q = 0; q < 8; ++q) { const int t = t0 + q * nb; if (t < ntile) { const int k0 = (t % nkt) * 64, n0 = (t / nkt) * 32;
;             const int j = tid >> 4, ii = (tid & 15) * 4; const LAS float* tp = tile + q * 2080 + j * 65 + ii;
;             u32x2 o; o.x = cvt_pk_bf16(tp[0], tp[1]); o.y = cvt_pk_bf16(tp[2], tp[3]);
;             *(u32x2*)(out + (size_t)(n0 + j) * K + k0 + ii) = o; } }
.LBB0_85:
	v_add_u32_e32 v18, s30, v20
	s_waitcnt lgkmcnt(0)
	s_barrier
	ds_read2_b32 v[14:15], v21 offset1:1
	v_ashrrev_i32_e32 v19, 31, v18
	ds_read2_b32 v[16:17], v21 offset0:2 offset1:3
	s_waitcnt lgkmcnt(1)
	v_cvt_pk_bf16_f32 v14, v14, v15
	s_add_i32 s34, s71, s86
	v_lshlrev_b64 v[18:19], 12, v[18:19]
	s_waitcnt lgkmcnt(0)
	v_cvt_pk_bf16_f32 v15, v16, v17
	v_lshl_add_u64 v[16:17], s[28:29], 0, v[18:19]
	s_ashr_i32 s35, s34, 31
	v_lshl_add_u64 v[16:17], s[34:35], 1, v[16:17]
	v_lshlrev_b32_e32 v6, 1, v4
	v_lshl_add_u64 v[16:17], v[16:17], 0, v[6:7]
	s_and_b64 vcc, exec, s[12:13]
	global_store_dwordx2 v[16:17], v[14:15], off
	s_cbranch_vccz .LBB0_98
	s_and_b64 vcc, exec, s[10:11]
	s_cbranch_vccz .LBB0_99

; #define LAS __attribute__((address_space(3)))
; DI unsigned cvt_pk_bf16(float lo, float hi) { unsigned r; asm volatile("v_cvt_pk_bf16_f32 %0, %1, %2" : "=v"(r) : "v"(lo), "v"(hi)); return r; }
; DI void transpose_w(const float* __restrict__ w, const float* __restrict__ rowscale, bf16_t* __restrict__ out, int K, int N, int bid, int nb, LAS float* tile) {
;     ...
;         for (int q = 0; q < 8; ++q) { const int t = t0 + q * nb; if (t < ntile) { const int k0 = (t % nkt) * 64, n0 = (t / nkt) * 32;
;             const int j = tid >> 4, ii = (tid & 15) * 4; const LAS float* tp = tile + q * 2080 + j * 65 + ii;
;             u32x2 o; o.x = cvt_pk_bf16(tp[0], tp[1]); o.y = cvt_pk_bf16(tp[2], tp[3]);
;             *(u32x2*)(out + (size_t)(n0 + j) * K + k0 + ii) = o; } }
.LBB0_98:
	s_ashr_i32 s12, s31, 31
	v_add_u32_e32 v14, 0x2080, v21
	s_lshr_b32 s12, s12, 27
	ds_read2_b32 v[14:15], v14 offset1:1
	v_add_u32_e32 v16, 0x2088, v21
	s_add_i32 s12, s31, s12
	ds_read2_b32 v[16:17], v16 offset1:1
	s_waitcnt lgkmcnt(1)
	v_cvt_pk_bf16_f32 v14, v14, v15
	s_and_b32 s13, s12, 0xffffffe0
	s_waitcnt lgkmcnt(0)
	v_cvt_pk_bf16_f32 v15, v16, v17
	v_add_u32_e32 v16, s13, v20
	s_sub_i32 s12, s31, s13
	v_ashrrev_i32_e32 v17, 31, v16
	s_lshl_b32 s12, s12, 6
	v_lshlrev_b64 v[16:17], 12, v[16:17]
	v_lshl_add_u64 v[16:17], s[28:29], 0, v[16:17]
	s_ashr_i32 s13, s12, 31
	v_lshl_add_u64 v[16:17], s[12:13], 1, v[16:17]
	v_lshl_add_u64 v[16:17], v[16:17], 0, v[6:7]
	global_store_dwordx2 v[16:17], v[14:15], off
	s_and_b64 vcc, exec, s[10:11]
	s_cbranch_vccnz .LBB0_87
.LBB0_99:
	s_ashr_i32 s10, s84, 31
	v_add_u32_e32 v14, 0x4100, v21
	s_lshr_b32 s10, s10, 27
	ds_read2_b32 v[14:15], v14 offset1:1
	v_add_u32_e32 v16, 0x4108, v21
	s_add_i32 s10, s84, s10
	ds_read2_b32 v[16:17], v16 offset1:1
	s_waitcnt lgkmcnt(1)
	v_cvt_pk_bf16_f32 v14, v14, v15
	s_and_b32 s11, s10, 0xffffffe0
	s_waitcnt lgkmcnt(0)
	v_cvt_pk_bf16_f32 v15, v16, v17
	v_add_u32_e32 v16, s11, v20
	s_sub_i32 s10, s84, s11
	v_ashrrev_i32_e32 v17, 31, v16
	s_lshl_b32 s10, s10, 6
	v_lshlrev_b64 v[16:17], 12, v[16:17]
	v_lshl_add_u64 v[16:17], s[28:29], 0, v[16:17]
	s_ashr_i32 s11, s10, 31
	v_lshl_add_u64 v[16:17], s[10:11], 1, v[16:17]
	v_lshl_add_u64 v[16:17], v[16:17], 0, v[6:7]
	global_store_dwordx2 v[16:17], v[14:15], off
	s_and_b64 vcc, exec, s[8:9]
	s_cbranch_vccnz .LBB0_88
.LBB0_100:
	s_ashr_i32 s8, s85, 31
	v_add_u32_e32 v14, 0x6180, v21
	s_lshr_b32 s8, s8, 27
	ds_read2_b32 v[14:15], v14 offset1:1
	v_add_u32_e32 v16, 0x6188, v21
	s_add_i32 s8, s85, s8
	ds_read2_b32 v[16:17], v16 offset1:1
	s_waitcnt lgkmcnt(1)
	v_cvt_pk_bf16_f32 v14, v14, v15
	s_and_b32 s9, s8, 0xffffffe0
	s_waitcnt lgkmcnt(0)
	v_cvt_pk_bf16_f32 v15, v16, v17
	v_add_u32_e32 v16, s9, v20
	s_sub_i32 s8, s85, s9
	v_ashrrev_i32_e32 v17, 31, v16
	s_lshl_b32 s8, s8, 6
	v_lshlrev_b64 v[16:17], 12, v[16:17]
	v_lshl_add_u64 v[16:17], s[28:29], 0, v[16:17]
	s_ashr_i32 s9, s8, 31
	v_lshl_add_u64 v[16:17], s[8:9], 1, v[16:17]
	v_lshl_add_u64 v[16:17], v[16:17], 0, v[6:7]
	global_store_dwordx2 v[16:17], v[14:15], off
	s_and_b64 vcc, exec, s[6:7]
	s_cbranch_vccnz .LBB0_89
.LBB0_101:
	s_ashr_i32 s6, s87, 31
	v_add_u32_e32 v14, 0x8200, v21
	s_lshr_b32 s6, s6, 27
	ds_read2_b32 v[14:15], v14 offset1:1
	v_add_u32_e32 v16, 0x8208, v21
	s_add_i32 s6, s87, s6
	ds_read2_b32 v[16:17], v16 offset1:1
	s_waitcnt lgkmcnt(1)
	v_cvt_pk_bf16_f32 v14, v14, v15
	s_and_b32 s7, s6, 0xffffffe0
	s_waitcnt lgkmcnt(0)
	v_cvt_pk_bf16_f32 v15, v16, v17
	v_add_u32_e32 v16, s7, v20
	s_sub_i32 s6, s87, s7
	v_ashrrev_i32_e32 v17, 31, v16
	s_lshl_b32 s6, s6, 6
	v_lshlrev_b64 v[16:17], 12, v[16:17]
	v_lshl_add_u64 v[16:17], s[28:29], 0, v[16:17]
	s_ashr_i32 s7, s6, 31
	v_lshl_add_u64 v[16:17], s[6:7], 1, v[16:17]
	v_lshl_add_u64 v[16:17], v[16:17], 0, v[6:7]
	global_store_dwordx2 v[16:17], v[14:15], off
	s_and_b64 vcc, exec, s[4:5]
	s_cbranch_vccnz .LBB0_90
.LBB0_102:
	s_ashr_i32 s4, s88, 31
	v_add_u32_e32 v14, 0xa280, v21
	s_lshr_b32 s4, s4, 27
	ds_read2_b32 v[14:15], v14 offset1:1
	v_add_u32_e32 v16, 0xa288, v21
	s_add_i32 s4, s88, s4
	ds_read2_b32 v[16:17], v16 offset1:1
	s_waitcnt lgkmcnt(1)
	v_cvt_pk_bf16_f32 v14, v14, v15
	s_and_b32 s5, s4, 0xffffffe0
	s_waitcnt lgkmcnt(0)
	v_cvt_pk_bf16_f32 v15, v16, v17
	v_add_u32_e32 v16, s5, v20
	s_sub_i32 s4, s88, s5
	v_ashrrev_i32_e32 v17, 31, v16
	s_lshl_b32 s4, s4, 6
	v_lshlrev_b64 v[16:17], 12, v[16:17]
	v_lshl_add_u64 v[16:17], s[28:29], 0, v[16:17]
	s_ashr_i32 s5, s4, 31
	v_lshl_add_u64 v[16:17], s[4:5], 1, v[16:17]
	v_lshl_add_u64 v[16:17], v[16:17], 0, v[6:7]
	global_store_dwordx2 v[16:17], v[14:15], off
	s_and_b64 vcc, exec, s[2:3]
	s_cbranch_vccnz .LBB0_91
.LBB0_103:
	s_ashr_i32 s2, s89, 31
	v_add_u32_e32 v14, 0xc300, v21
	s_lshr_b32 s2, s2, 27
	ds_read2_b32 v[14:15], v14 offset1:1
	v_add_u32_e32 v16, 0xc308, v21
	s_add_i32 s2, s89, s2
	ds_read2_b32 v[16:17], v16 offset1:1
	s_waitcnt lgkmcnt(1)
	v_cvt_pk_bf16_f32 v14, v14, v15
	s_and_b32 s3, s2, 0xffffffe0
	s_waitcnt lgkmcnt(0)
	v_cvt_pk_bf16_f32 v15, v16, v17
	v_add_u32_e32 v16, s3, v20
	s_sub_i32 s2, s89, s3
	v_ashrrev_i32_e32 v17, 31, v16
	s_lshl_b32 s2, s2, 6
	v_lshlrev_b64 v[16:17], 12, v[16:17]
	v_lshl_add_u64 v[16:17], s[28:29], 0, v[16:17]
	s_ashr_i32 s3, s2, 31
	v_lshl_add_u64 v[16:17], s[2:3], 1, v[16:17]
	v_lshl_add_u64 v[16:17], v[16:17], 0, v[6:7]
	global_store_dwordx2 v[16:17], v[14:15], off
	s_and_b64 vcc, exec, s[0:1]
	s_cbranch_vccnz .LBB0_5
.LBB0_104:
	s_ashr_i32 s0, s90, 31
	v_add_u32_e32 v14, 0xe380, v21
	s_lshr_b32 s0, s0, 27
	ds_read2_b32 v[14:15], v14 offset1:1
	v_add_u32_e32 v16, 0xe388, v21
	s_add_i32 s0, s90, s0
	ds_read2_b32 v[16:17], v16 offset1:1
	s_waitcnt lgkmcnt(1)
	v_cvt_pk_bf16_f32 v14, v14, v15
	s_and_b32 s1, s0, 0xffffffe0
	s_waitcnt lgkmcnt(0)
	v_cvt_pk_bf16_f32 v15, v16, v17
	v_add_u32_e32 v16, s1, v20
	s_sub_i32 s0, s90, s1
	v_ashrrev_i32_e32 v17, 31, v16
	s_lshl_b32 s0, s0, 6
	v_lshlrev_b64 v[16:17], 12, v[16:17]
	v_lshl_add_u64 v[16:17], s[28:29], 0, v[16:17]
	s_ashr_i32 s1, s0, 31
	v_lshl_add_u64 v[16:17], s[0:1], 1, v[16:17]
	v_lshl_add_u64 v[16:17], v[16:17], 0, v[6:7]
	global_store_dwordx2 v[16:17], v[14:15], off
	s_branch .LBB0_5
